# GEMM K-loop: split vmcnt waits (8 at L4/L8, 10 at L2/L6) so the tightest LDS-DMA pieces get two more phases to land; on top of v046
# baseline (speedup 1.0000x reference)
; #define PG8_STAGE(bufoff, gbase, voff) do { _Pragma("unroll") for (int _i = 0; _i < 2; ++_i) \
;         __builtin_amdgcn_global_load_lds((const unsigned*)((const char*)(gbase) + (voff)[_i]), (LAS unsigned*)(lds + (bufoff) + ldsw + _i * 8192), 16, 0, 0); } while (0)
; #define PG8_LDA(dst, b, h) do { _Pragma("unroll") for (int m = 0; m < 4; ++m) _Pragma("unroll") for (int k = 0; k < 2; ++k) dst[m][k] = *(const LAS bf16x8*)(lds + PG8_SA(b, h) + aoff + m * 2048 + k * 1024); } while (0)
; #define PG8_LDB(dst, b, h) do { _Pragma("unroll") for (int n = 0; n < 2; ++n) _Pragma("unroll") for (int k = 0; k < 2; ++k) dst[n][k] = *(const LAS bf16x8*)(lds + PG8_SB(b, h) + boff + n * 2048 + k * 1024); } while (0)
; #define PG8_MMA(ai, bj, At, Bt) do { __builtin_amdgcn_s_setprio(1); _Pragma("unroll") for (int m = 0; m < 4; ++m) _Pragma("unroll") for (int n = 0; n < 2; ++n) _Pragma("unroll") for (int k = 0; k < 2; ++k) \
;         acc[ai][bj][m][n] = __builtin_amdgcn_mfma_f32_16x16x32_bf16(Bt[n][k], At[m][k], acc[ai][bj][m][n], 0, 0, 0); __builtin_amdgcn_s_setprio(0); } while (0)
; #define PG8_WAIT_V(n) asm volatile("s_waitcnt vmcnt(" #n ")" ::: "memory")
; #define PG8_WAIT_L(n) asm volatile("s_waitcnt lgkmcnt(" #n ")" ::: "memory")
; template <class Epi, class Sched>
; __device__ __forceinline__ void gemm_phase(LAS unsigned char* lds, const Gemm g, const Sched& S, const Epi& E) {
;     ...
;         for (int t = 0; t < nt; t += 2) {
;             const bool last = (t == nt - 2);
;             const char* a1 = cA + (size_t)(t + 1) * kstep;
;             const char* a2 = last ? nA : cA + (size_t)(t + 2) * kstep; const char* b2 = last ? nB : cB + (size_t)(t + 2) * kstep;
;             const char* a3 = a2 + kstep; const char* b3 = b2 + kstep;
;             PG8_LDB(B0, 0, 0); PG8_SCHED; PG8_LDA(At, 0, 0); PG8_STAGE(PG8_SA(1, 1), a1 + hstep, voffA);
;             PG8_WAIT_L(8); PG8_BAR; PG8_WAIT_L(0); PG8_MMA(0, 0, At, B0); PG8_BAR; PG8_SCHED;
;             PG8_LDB(B1, 0, 1); PG8_STAGE(PG8_SB(0, 0), b2, voffB);
;             PG8_BAR; PG8_WAIT_L(0); PG8_MMA(0, 1, At, B1); PG8_BAR;
;             PG8_LDA(At, 0, 1); PG8_STAGE(PG8_SA(0, 0), a2, voffA);
;             PG8_BAR; PG8_WAIT_L(0); PG8_MMA(1, 0, At, B0); PG8_BAR; PG8_SCHED;
;             PG8_STAGE(PG8_SB(0, 1), b2 + hstep, voffB);
;             PG8_WAIT_V(6); PG8_BAR; PG8_MMA(1, 1, At, B1); PG8_BAR;
.LBB0_232:
	s_add_i32 s33, s29, 2
	s_add_u32 s30, s26, 0x80
	s_addc_u32 s31, s27, 0
	s_add_i32 s42, 0, 0x10000
	ds_read_b128 v[128:131], v216
	ds_read_b128 v[132:135], v216 offset:1024
	ds_read_b128 v[136:139], v216 offset:2048
	ds_read_b128 v[140:143], v216 offset:3072
	s_cmp_eq_u32 s76, s29
	s_cselect_b32 s31, s1, s31
	s_cselect_b32 s30, s0, s30
	s_cselect_b32 s35, s9, s25
	s_cselect_b32 s34, s8, s24
	s_add_i32 m0, s67, 0xc000
	ds_read_b128 v[144:147], v235
	ds_read_b128 v[148:151], v235 offset:1024
	ds_read_b128 v[152:155], v235 offset:2048
	ds_read_b128 v[156:159], v235 offset:3072
	ds_read_b128 v[160:163], v235 offset:4096
	ds_read_b128 v[164:167], v235 offset:5120
	ds_read_b128 v[168:171], v235 offset:6144
	ds_read_b128 v[172:175], v235 offset:7168
	global_load_lds_dwordx4 v194, s[26:27]
	s_add_i32 m0, s67, 0xe000
	s_nop 0
	global_load_lds_dwordx4 v192, s[26:27]
	s_waitcnt lgkmcnt(8)
	s_barrier
	s_waitcnt lgkmcnt(0)
	s_waitcnt lgkmcnt(0)
	v_mfma_f32_16x16x32_bf16 v[120:123], v[128:131], v[144:147], v[120:123]
	v_mfma_f32_16x16x32_bf16 v[112:115], v[136:139], v[144:147], v[112:115]
	v_mfma_f32_16x16x32_bf16 v[104:107], v[128:131], v[152:155], v[104:107]
	v_mfma_f32_16x16x32_bf16 v[96:99], v[136:139], v[152:155], v[96:99]
	v_mfma_f32_16x16x32_bf16 v[88:91], v[128:131], v[160:163], v[88:91]
	v_mfma_f32_16x16x32_bf16 v[80:83], v[136:139], v[160:163], v[80:83]
	v_mfma_f32_16x16x32_bf16 v[72:75], v[128:131], v[168:171], v[72:75]
	v_mfma_f32_16x16x32_bf16 v[64:67], v[136:139], v[168:171], v[64:67]
	v_mfma_f32_16x16x32_bf16 v[120:123], v[132:135], v[148:151], v[120:123]
	v_mfma_f32_16x16x32_bf16 v[112:115], v[140:143], v[148:151], v[112:115]
	v_mfma_f32_16x16x32_bf16 v[104:107], v[132:135], v[156:159], v[104:107]
	v_mfma_f32_16x16x32_bf16 v[96:99], v[140:143], v[156:159], v[96:99]
	v_mfma_f32_16x16x32_bf16 v[88:91], v[132:135], v[164:167], v[88:91]
	v_mfma_f32_16x16x32_bf16 v[80:83], v[140:143], v[164:167], v[80:83]
	v_mfma_f32_16x16x32_bf16 v[72:75], v[132:135], v[172:175], v[72:75]
	v_mfma_f32_16x16x32_bf16 v[64:67], v[140:143], v[172:175], v[64:67]
	s_barrier
	s_add_i32 s29, 0, 0x14000
	s_add_i32 s42, s42, s66
	s_mov_b32 m0, s42
	ds_read_b128 v[176:179], v217
	ds_read_b128 v[180:183], v217 offset:1024
	ds_read_b128 v[196:199], v217 offset:2048
	ds_read_b128 v[200:203], v217 offset:3072
	s_add_u32 s36, s34, 0x80
	s_addc_u32 s37, s35, 0
	global_load_lds_dwordx4 v188, s[34:35]
	s_add_i32 m0, s42, 0x2000
	s_nop 0
	global_load_lds_dwordx4 v184, s[34:35]
	s_waitcnt vmcnt(10)
	s_barrier
	s_waitcnt lgkmcnt(0)
	s_waitcnt lgkmcnt(0)
	v_mfma_f32_16x16x32_bf16 v[124:127], v[176:179], v[144:147], v[124:127]
	v_mfma_f32_16x16x32_bf16 v[116:119], v[196:199], v[144:147], v[116:119]
	v_mfma_f32_16x16x32_bf16 v[108:111], v[176:179], v[152:155], v[108:111]
	v_mfma_f32_16x16x32_bf16 v[100:103], v[196:199], v[152:155], v[100:103]
	v_mfma_f32_16x16x32_bf16 v[92:95], v[176:179], v[160:163], v[92:95]
	v_mfma_f32_16x16x32_bf16 v[84:87], v[196:199], v[160:163], v[84:87]
	v_mfma_f32_16x16x32_bf16 v[76:79], v[176:179], v[168:171], v[76:79]
	v_mfma_f32_16x16x32_bf16 v[68:71], v[196:199], v[168:171], v[68:71]
	v_mfma_f32_16x16x32_bf16 v[124:127], v[180:183], v[148:151], v[124:127]
	v_mfma_f32_16x16x32_bf16 v[116:119], v[200:203], v[148:151], v[116:119]
	v_mfma_f32_16x16x32_bf16 v[108:111], v[180:183], v[156:159], v[108:111]
	v_mfma_f32_16x16x32_bf16 v[100:103], v[200:203], v[156:159], v[100:103]
	v_mfma_f32_16x16x32_bf16 v[92:95], v[180:183], v[164:167], v[92:95]
	v_mfma_f32_16x16x32_bf16 v[84:87], v[200:203], v[164:167], v[84:87]
	v_mfma_f32_16x16x32_bf16 v[76:79], v[180:183], v[172:175], v[76:79]
	v_mfma_f32_16x16x32_bf16 v[68:71], v[200:203], v[172:175], v[68:71]
	s_mov_b32 m0, s67
	s_barrier
	ds_read_b128 v[144:147], v235 offset:16384
	ds_read_b128 v[148:151], v235 offset:17408
	ds_read_b128 v[152:155], v235 offset:18432
	ds_read_b128 v[156:159], v235 offset:19456
	ds_read_b128 v[160:163], v235 offset:20480
	ds_read_b128 v[164:167], v235 offset:21504
	ds_read_b128 v[168:171], v235 offset:22528
	ds_read_b128 v[172:175], v235 offset:23552
	s_add_u32 s54, s30, 0x80
	s_addc_u32 s55, s31, 0
	global_load_lds_dwordx4 v188, s[30:31]
	s_mov_b32 m0, s68
	s_nop 0
	global_load_lds_dwordx4 v184, s[30:31]
	s_barrier
	s_waitcnt lgkmcnt(0)
	s_waitcnt lgkmcnt(0)
	v_mfma_f32_16x16x32_bf16 v[56:59], v[128:131], v[144:147], v[56:59]
	v_mfma_f32_16x16x32_bf16 v[48:51], v[136:139], v[144:147], v[48:51]
	v_mfma_f32_16x16x32_bf16 v[40:43], v[128:131], v[152:155], v[40:43]
	v_mfma_f32_16x16x32_bf16 v[32:35], v[136:139], v[152:155], v[32:35]
	v_mfma_f32_16x16x32_bf16 v[24:27], v[128:131], v[160:163], v[24:27]
	v_mfma_f32_16x16x32_bf16 v[16:19], v[136:139], v[160:163], v[16:19]
	v_mfma_f32_16x16x32_bf16 v[8:11], v[128:131], v[168:171], v[8:11]
	v_mfma_f32_16x16x32_bf16 v[0:3], v[136:139], v[168:171], v[0:3]
	v_mfma_f32_16x16x32_bf16 v[56:59], v[132:135], v[148:151], v[56:59]
	v_mfma_f32_16x16x32_bf16 v[48:51], v[140:143], v[148:151], v[48:51]
	v_mfma_f32_16x16x32_bf16 v[40:43], v[132:135], v[156:159], v[40:43]
	v_mfma_f32_16x16x32_bf16 v[32:35], v[140:143], v[156:159], v[32:35]
	v_mfma_f32_16x16x32_bf16 v[24:27], v[132:135], v[164:167], v[24:27]
	v_mfma_f32_16x16x32_bf16 v[16:19], v[140:143], v[164:167], v[16:19]
	v_mfma_f32_16x16x32_bf16 v[8:11], v[132:135], v[172:175], v[8:11]
	v_mfma_f32_16x16x32_bf16 v[0:3], v[140:143], v[172:175], v[0:3]
	s_barrier
	s_add_u32 s34, s34, s12
	s_addc_u32 s35, s35, s13
	s_add_u32 s84, s34, 0x80
	s_addc_u32 s85, s35, 0
	s_add_i32 s29, s29, s66
	s_mov_b32 m0, s29
	s_nop 0
	global_load_lds_dwordx4 v188, s[34:35]
	s_add_i32 m0, s29, 0x2000
	s_nop 0
	global_load_lds_dwordx4 v184, s[34:35]
	s_waitcnt vmcnt(8)
	s_barrier
; #define PG8_STAGE(bufoff, gbase, voff) do { _Pragma("unroll") for (int _i = 0; _i < 2; ++_i) \
;         __builtin_amdgcn_global_load_lds((const unsigned*)((const char*)(gbase) + (voff)[_i]), (LAS unsigned*)(lds + (bufoff) + ldsw + _i * 8192), 16, 0, 0); } while (0)
; #define PG8_LDA(dst, b, h) do { _Pragma("unroll") for (int m = 0; m < 4; ++m) _Pragma("unroll") for (int k = 0; k < 2; ++k) dst[m][k] = *(const LAS bf16x8*)(lds + PG8_SA(b, h) + aoff + m * 2048 + k * 1024); } while (0)
; #define PG8_LDB(dst, b, h) do { _Pragma("unroll") for (int n = 0; n < 2; ++n) _Pragma("unroll") for (int k = 0; k < 2; ++k) dst[n][k] = *(const LAS bf16x8*)(lds + PG8_SB(b, h) + boff + n * 2048 + k * 1024); } while (0)
; #define PG8_MMA(ai, bj, At, Bt) do { __builtin_amdgcn_s_setprio(1); _Pragma("unroll") for (int m = 0; m < 4; ++m) _Pragma("unroll") for (int n = 0; n < 2; ++n) _Pragma("unroll") for (int k = 0; k < 2; ++k) \
;         acc[ai][bj][m][n] = __builtin_amdgcn_mfma_f32_16x16x32_bf16(Bt[n][k], At[m][k], acc[ai][bj][m][n], 0, 0, 0); __builtin_amdgcn_s_setprio(0); } while (0)
; #define PG8_WAIT_V(n) asm volatile("s_waitcnt vmcnt(" #n ")" ::: "memory")
; #define PG8_WAIT_L(n) asm volatile("s_waitcnt lgkmcnt(" #n ")" ::: "memory")
; #define PG8_BAR __builtin_amdgcn_s_barrier()
; #define PG8_SCHED __builtin_amdgcn_sched_barrier(0)
; template <class Epi, class Sched>
; __device__ __forceinline__ void gemm_phase(LAS unsigned char* lds, const Gemm g, const Sched& S, const Epi& E) {
;     ...
;             PG8_WAIT_V(6); PG8_BAR; PG8_MMA(1, 1, At, B1); PG8_BAR;
;             PG8_LDB(B0, 1, 0); PG8_SCHED; PG8_LDA(At, 1, 0); PG8_STAGE(PG8_SA(0, 1), a2 + hstep, voffA);
;             PG8_WAIT_L(8); PG8_BAR; PG8_WAIT_L(0); PG8_MMA(0, 0, At, B0); PG8_BAR; PG8_SCHED;
;             PG8_LDB(B1, 1, 1); PG8_STAGE(PG8_SB(1, 0), b3, voffB);
	v_mfma_f32_16x16x32_bf16 v[60:63], v[176:179], v[144:147], v[60:63]
	v_mfma_f32_16x16x32_bf16 v[52:55], v[196:199], v[144:147], v[52:55]
	v_mfma_f32_16x16x32_bf16 v[44:47], v[176:179], v[152:155], v[44:47]
	v_mfma_f32_16x16x32_bf16 v[36:39], v[196:199], v[152:155], v[36:39]
	v_mfma_f32_16x16x32_bf16 v[28:31], v[176:179], v[160:163], v[28:31]
	v_mfma_f32_16x16x32_bf16 v[20:23], v[196:199], v[160:163], v[20:23]
	v_mfma_f32_16x16x32_bf16 v[12:15], v[176:179], v[168:171], v[12:15]
	v_mfma_f32_16x16x32_bf16 v[4:7], v[196:199], v[168:171], v[4:7]
	v_mfma_f32_16x16x32_bf16 v[60:63], v[180:183], v[148:151], v[60:63]
	v_mfma_f32_16x16x32_bf16 v[52:55], v[200:203], v[148:151], v[52:55]
	v_mfma_f32_16x16x32_bf16 v[44:47], v[180:183], v[156:159], v[44:47]
	v_mfma_f32_16x16x32_bf16 v[36:39], v[200:203], v[156:159], v[36:39]
	v_mfma_f32_16x16x32_bf16 v[28:31], v[180:183], v[164:167], v[28:31]
	v_mfma_f32_16x16x32_bf16 v[20:23], v[200:203], v[164:167], v[20:23]
	v_mfma_f32_16x16x32_bf16 v[12:15], v[180:183], v[172:175], v[12:15]
	v_mfma_f32_16x16x32_bf16 v[4:7], v[200:203], v[172:175], v[4:7]
	s_add_i32 s29, 0, 0x18000
	s_barrier
	ds_read_b128 v[128:131], v218
	ds_read_b128 v[132:135], v218 offset:1024
	ds_read_b128 v[136:139], v218 offset:2048
	ds_read_b128 v[140:143], v218 offset:3072
	s_add_u32 s30, s30, s12
	s_addc_u32 s31, s31, s13
	s_mov_b32 m0, s69
	ds_read_b128 v[144:147], v235 offset:32768
	ds_read_b128 v[148:151], v235 offset:33792
	ds_read_b128 v[152:155], v235 offset:34816
	ds_read_b128 v[156:159], v235 offset:35840
	ds_read_b128 v[160:163], v235 offset:36864
	ds_read_b128 v[164:167], v235 offset:37888
	ds_read_b128 v[168:171], v235 offset:38912
	ds_read_b128 v[172:175], v235 offset:39936
	global_load_lds_dwordx4 v188, s[30:31]
	s_mov_b32 m0, s70
	s_nop 0
	global_load_lds_dwordx4 v184, s[30:31]
	s_waitcnt lgkmcnt(8)
	s_barrier
	s_waitcnt lgkmcnt(0)
	s_waitcnt lgkmcnt(0)
	v_mfma_f32_16x16x32_bf16 v[120:123], v[128:131], v[144:147], v[120:123]
	v_mfma_f32_16x16x32_bf16 v[112:115], v[136:139], v[144:147], v[112:115]
	v_mfma_f32_16x16x32_bf16 v[104:107], v[128:131], v[152:155], v[104:107]
	v_mfma_f32_16x16x32_bf16 v[96:99], v[136:139], v[152:155], v[96:99]
	v_mfma_f32_16x16x32_bf16 v[88:91], v[128:131], v[160:163], v[88:91]
	v_mfma_f32_16x16x32_bf16 v[80:83], v[136:139], v[160:163], v[80:83]
	v_mfma_f32_16x16x32_bf16 v[72:75], v[128:131], v[168:171], v[72:75]
	v_mfma_f32_16x16x32_bf16 v[64:67], v[136:139], v[168:171], v[64:67]
	v_mfma_f32_16x16x32_bf16 v[120:123], v[132:135], v[148:151], v[120:123]
	v_mfma_f32_16x16x32_bf16 v[112:115], v[140:143], v[148:151], v[112:115]
	v_mfma_f32_16x16x32_bf16 v[104:107], v[132:135], v[156:159], v[104:107]
	v_mfma_f32_16x16x32_bf16 v[96:99], v[140:143], v[156:159], v[96:99]
	v_mfma_f32_16x16x32_bf16 v[88:91], v[132:135], v[164:167], v[88:91]
	v_mfma_f32_16x16x32_bf16 v[80:83], v[140:143], v[164:167], v[80:83]
	v_mfma_f32_16x16x32_bf16 v[72:75], v[132:135], v[172:175], v[72:75]
	v_mfma_f32_16x16x32_bf16 v[64:67], v[140:143], v[172:175], v[64:67]
	s_barrier
	s_add_i32 s30, 0, 0x1c000
	s_add_i32 s29, s29, s66
	s_mov_b32 m0, s29
	ds_read_b128 v[176:179], v219
	ds_read_b128 v[180:183], v219 offset:1024
	ds_read_b128 v[196:199], v219 offset:2048
	ds_read_b128 v[200:203], v219 offset:3072
	global_load_lds_dwordx4 v188, s[36:37]
	s_add_i32 m0, s29, 0x2000
	s_nop 0
	global_load_lds_dwordx4 v184, s[36:37]
	s_waitcnt vmcnt(10)
	s_barrier
; #define PG8_STAGE(bufoff, gbase, voff) do { _Pragma("unroll") for (int _i = 0; _i < 2; ++_i) \
;         __builtin_amdgcn_global_load_lds((const unsigned*)((const char*)(gbase) + (voff)[_i]), (LAS unsigned*)(lds + (bufoff) + ldsw + _i * 8192), 16, 0, 0); } while (0)
; #define PG8_LDA(dst, b, h) do { _Pragma("unroll") for (int m = 0; m < 4; ++m) _Pragma("unroll") for (int k = 0; k < 2; ++k) dst[m][k] = *(const LAS bf16x8*)(lds + PG8_SA(b, h) + aoff + m * 2048 + k * 1024); } while (0)
; #define PG8_LDB(dst, b, h) do { _Pragma("unroll") for (int n = 0; n < 2; ++n) _Pragma("unroll") for (int k = 0; k < 2; ++k) dst[n][k] = *(const LAS bf16x8*)(lds + PG8_SB(b, h) + boff + n * 2048 + k * 1024); } while (0)
; #define PG8_MMA(ai, bj, At, Bt) do { __builtin_amdgcn_s_setprio(1); _Pragma("unroll") for (int m = 0; m < 4; ++m) _Pragma("unroll") for (int n = 0; n < 2; ++n) _Pragma("unroll") for (int k = 0; k < 2; ++k) \
;         acc[ai][bj][m][n] = __builtin_amdgcn_mfma_f32_16x16x32_bf16(Bt[n][k], At[m][k], acc[ai][bj][m][n], 0, 0, 0); __builtin_amdgcn_s_setprio(0); } while (0)
; #define PG8_WAIT_V(n) asm volatile("s_waitcnt vmcnt(" #n ")" ::: "memory")
; #define PG8_WAIT_L(n) asm volatile("s_waitcnt lgkmcnt(" #n ")" ::: "memory")
; #define PG8_BAR __builtin_amdgcn_s_barrier()
; #define PG8_SCHED __builtin_amdgcn_sched_barrier(0)
; template <class Epi, class Sched>
; __device__ __forceinline__ void gemm_phase(LAS unsigned char* lds, const Gemm g, const Sched& S, const Epi& E) {
;     ...
;             PG8_LDB(B1, 1, 1); PG8_STAGE(PG8_SB(1, 0), b3, voffB);
;             PG8_BAR; PG8_WAIT_L(0); PG8_MMA(0, 1, At, B1); PG8_BAR;
;             PG8_LDA(At, 1, 1); PG8_STAGE(PG8_SA(1, 0), a3, voffA);
;             PG8_BAR; PG8_WAIT_L(0); PG8_MMA(1, 0, At, B0); PG8_BAR; PG8_SCHED;
;             PG8_STAGE(PG8_SB(1, 1), b3 + hstep, voffB);
;             PG8_WAIT_V(6); PG8_BAR; PG8_MMA(1, 1, At, B1); PG8_BAR;
;         }
	s_waitcnt lgkmcnt(0)
	s_waitcnt lgkmcnt(0)
	v_mfma_f32_16x16x32_bf16 v[124:127], v[176:179], v[144:147], v[124:127]
	v_mfma_f32_16x16x32_bf16 v[116:119], v[196:199], v[144:147], v[116:119]
	v_mfma_f32_16x16x32_bf16 v[108:111], v[176:179], v[152:155], v[108:111]
	v_mfma_f32_16x16x32_bf16 v[100:103], v[196:199], v[152:155], v[100:103]
	v_mfma_f32_16x16x32_bf16 v[92:95], v[176:179], v[160:163], v[92:95]
	v_mfma_f32_16x16x32_bf16 v[84:87], v[196:199], v[160:163], v[84:87]
	v_mfma_f32_16x16x32_bf16 v[76:79], v[176:179], v[168:171], v[76:79]
	v_mfma_f32_16x16x32_bf16 v[68:71], v[196:199], v[168:171], v[68:71]
	v_mfma_f32_16x16x32_bf16 v[124:127], v[180:183], v[148:151], v[124:127]
	v_mfma_f32_16x16x32_bf16 v[116:119], v[200:203], v[148:151], v[116:119]
	v_mfma_f32_16x16x32_bf16 v[108:111], v[180:183], v[156:159], v[108:111]
	v_mfma_f32_16x16x32_bf16 v[100:103], v[200:203], v[156:159], v[100:103]
	v_mfma_f32_16x16x32_bf16 v[92:95], v[180:183], v[164:167], v[92:95]
	v_mfma_f32_16x16x32_bf16 v[84:87], v[200:203], v[164:167], v[84:87]
	v_mfma_f32_16x16x32_bf16 v[76:79], v[180:183], v[172:175], v[76:79]
	v_mfma_f32_16x16x32_bf16 v[68:71], v[200:203], v[172:175], v[68:71]
	s_mov_b32 m0, s18
	s_barrier
	ds_read_b128 v[144:147], v235 offset:49152
	ds_read_b128 v[148:151], v235 offset:50176
	ds_read_b128 v[152:155], v235 offset:51200
	ds_read_b128 v[156:159], v235 offset:52224
	ds_read_b128 v[160:163], v235 offset:53248
	ds_read_b128 v[164:167], v235 offset:54272
	ds_read_b128 v[168:171], v235 offset:55296
	ds_read_b128 v[172:175], v235 offset:56320
	global_load_lds_dwordx4 v188, s[54:55]
	s_mov_b32 m0, s75
	s_nop 0
	global_load_lds_dwordx4 v184, s[54:55]
	s_barrier
	s_waitcnt lgkmcnt(0)
	s_waitcnt lgkmcnt(0)
	v_mfma_f32_16x16x32_bf16 v[56:59], v[128:131], v[144:147], v[56:59]
	v_mfma_f32_16x16x32_bf16 v[48:51], v[136:139], v[144:147], v[48:51]
	v_mfma_f32_16x16x32_bf16 v[40:43], v[128:131], v[152:155], v[40:43]
	v_mfma_f32_16x16x32_bf16 v[32:35], v[136:139], v[152:155], v[32:35]
	v_mfma_f32_16x16x32_bf16 v[24:27], v[128:131], v[160:163], v[24:27]
	v_mfma_f32_16x16x32_bf16 v[16:19], v[136:139], v[160:163], v[16:19]
	v_mfma_f32_16x16x32_bf16 v[8:11], v[128:131], v[168:171], v[8:11]
	v_mfma_f32_16x16x32_bf16 v[0:3], v[136:139], v[168:171], v[0:3]
	v_mfma_f32_16x16x32_bf16 v[56:59], v[132:135], v[148:151], v[56:59]
	v_mfma_f32_16x16x32_bf16 v[48:51], v[140:143], v[148:151], v[48:51]
	v_mfma_f32_16x16x32_bf16 v[40:43], v[132:135], v[156:159], v[40:43]
	v_mfma_f32_16x16x32_bf16 v[32:35], v[140:143], v[156:159], v[32:35]
	v_mfma_f32_16x16x32_bf16 v[24:27], v[132:135], v[164:167], v[24:27]
	v_mfma_f32_16x16x32_bf16 v[16:19], v[140:143], v[164:167], v[16:19]
	v_mfma_f32_16x16x32_bf16 v[8:11], v[132:135], v[172:175], v[8:11]
	v_mfma_f32_16x16x32_bf16 v[0:3], v[140:143], v[172:175], v[0:3]
	s_barrier
	s_add_i32 s29, s30, s66
	s_mov_b32 m0, s29
	s_nop 0
	global_load_lds_dwordx4 v188, s[84:85]
	s_add_i32 m0, s29, 0x2000
	s_nop 0
	global_load_lds_dwordx4 v184, s[84:85]
	s_waitcnt vmcnt(8)
	s_barrier
	v_mfma_f32_16x16x32_bf16 v[60:63], v[176:179], v[144:147], v[60:63]
	v_mfma_f32_16x16x32_bf16 v[52:55], v[196:199], v[144:147], v[52:55]
	v_mfma_f32_16x16x32_bf16 v[44:47], v[176:179], v[152:155], v[44:47]
	v_mfma_f32_16x16x32_bf16 v[36:39], v[196:199], v[152:155], v[36:39]
	v_mfma_f32_16x16x32_bf16 v[28:31], v[176:179], v[160:163], v[28:31]
	v_mfma_f32_16x16x32_bf16 v[20:23], v[196:199], v[160:163], v[20:23]
	v_mfma_f32_16x16x32_bf16 v[12:15], v[176:179], v[168:171], v[12:15]
	v_mfma_f32_16x16x32_bf16 v[4:7], v[196:199], v[168:171], v[4:7]
	v_mfma_f32_16x16x32_bf16 v[60:63], v[180:183], v[148:151], v[60:63]
	v_mfma_f32_16x16x32_bf16 v[52:55], v[200:203], v[148:151], v[52:55]
	v_mfma_f32_16x16x32_bf16 v[44:47], v[180:183], v[156:159], v[44:47]
	v_mfma_f32_16x16x32_bf16 v[36:39], v[200:203], v[156:159], v[36:39]
	v_mfma_f32_16x16x32_bf16 v[28:31], v[180:183], v[164:167], v[28:31]
	v_mfma_f32_16x16x32_bf16 v[20:23], v[200:203], v[164:167], v[20:23]
	v_mfma_f32_16x16x32_bf16 v[12:15], v[180:183], v[172:175], v[12:15]
	v_mfma_f32_16x16x32_bf16 v[4:7], v[200:203], v[172:175], v[4:7]
	s_add_u32 s24, s24, 0x100
	s_addc_u32 s25, s25, 0
	s_add_u32 s26, s26, 0x100
	s_addc_u32 s27, s27, 0
	s_cmp_ge_i32 s33, s74
	s_mov_b32 s29, s33
	s_barrier
	s_cbranch_scc0 .LBB0_232
	s_mov_b32 s42, s82
	s_branch .LBB0_235

; #define PG8_STAGE(bufoff, gbase, voff) do { _Pragma("unroll") for (int _i = 0; _i < 2; ++_i) \
;         __builtin_amdgcn_global_load_lds((const unsigned*)((const char*)(gbase) + (voff)[_i]), (LAS unsigned*)(lds + (bufoff) + ldsw + _i * 8192), 16, 0, 0); } while (0)
; #define PG8_LDA(dst, b, h) do { _Pragma("unroll") for (int m = 0; m < 4; ++m) _Pragma("unroll") for (int k = 0; k < 2; ++k) dst[m][k] = *(const LAS bf16x8*)(lds + PG8_SA(b, h) + aoff + m * 2048 + k * 1024); } while (0)
; #define PG8_LDB(dst, b, h) do { _Pragma("unroll") for (int n = 0; n < 2; ++n) _Pragma("unroll") for (int k = 0; k < 2; ++k) dst[n][k] = *(const LAS bf16x8*)(lds + PG8_SB(b, h) + boff + n * 2048 + k * 1024); } while (0)
; #define PG8_MMA(ai, bj, At, Bt) do { __builtin_amdgcn_s_setprio(1); _Pragma("unroll") for (int m = 0; m < 4; ++m) _Pragma("unroll") for (int n = 0; n < 2; ++n) _Pragma("unroll") for (int k = 0; k < 2; ++k) \
;         acc[ai][bj][m][n] = __builtin_amdgcn_mfma_f32_16x16x32_bf16(Bt[n][k], At[m][k], acc[ai][bj][m][n], 0, 0, 0); __builtin_amdgcn_s_setprio(0); } while (0)
; #define PG8_WAIT_V(n) asm volatile("s_waitcnt vmcnt(" #n ")" ::: "memory")
; #define PG8_WAIT_L(n) asm volatile("s_waitcnt lgkmcnt(" #n ")" ::: "memory")
; template <class Epi, class Sched>
; __device__ __forceinline__ void gemm_phase(LAS unsigned char* lds, const Gemm g, const Sched& S, const Epi& E) {
;     ...
;         for (int t = 0; t < nt; t += 2) {
;             const bool last = (t == nt - 2);
;             const char* a1 = cA + (size_t)(t + 1) * kstep;
;             const char* a2 = last ? nA : cA + (size_t)(t + 2) * kstep; const char* b2 = last ? nB : cB + (size_t)(t + 2) * kstep;
;             const char* a3 = a2 + kstep; const char* b3 = b2 + kstep;
;             PG8_LDB(B0, 0, 0); PG8_SCHED; PG8_LDA(At, 0, 0); PG8_STAGE(PG8_SA(1, 1), a1 + hstep, voffA);
;             PG8_WAIT_L(8); PG8_BAR; PG8_WAIT_L(0); PG8_MMA(0, 0, At, B0); PG8_BAR; PG8_SCHED;
;             PG8_LDB(B1, 0, 1); PG8_STAGE(PG8_SB(0, 0), b2, voffB);
;             PG8_BAR; PG8_WAIT_L(0); PG8_MMA(0, 1, At, B1); PG8_BAR;
;             PG8_LDA(At, 0, 1); PG8_STAGE(PG8_SA(0, 0), a2, voffA);
;             PG8_BAR; PG8_WAIT_L(0); PG8_MMA(1, 0, At, B0); PG8_BAR; PG8_SCHED;
;             PG8_STAGE(PG8_SB(0, 1), b2 + hstep, voffB);
;             PG8_WAIT_V(6); PG8_BAR; PG8_MMA(1, 1, At, B1); PG8_BAR;
.LBB0_339:
	s_add_i32 s30, s4, 2
	s_add_u32 s28, s0, 0x80
	s_addc_u32 s5, s1, 0
	s_add_i32 s31, 0, 0x10000
	ds_read_b128 v[128:131], v240
	ds_read_b128 v[132:135], v240 offset:1024
	ds_read_b128 v[136:139], v240 offset:2048
	ds_read_b128 v[140:143], v240 offset:3072
	s_cmp_eq_u32 s66, s4
	s_cselect_b32 s4, s18, s28
	s_cselect_b32 s5, s19, s5
	s_cselect_b32 s29, s27, s76
	s_cselect_b32 s28, s26, s75
	s_add_i32 m0, s50, 0xc000
	ds_read_b128 v[144:147], v221
	ds_read_b128 v[148:151], v221 offset:1024
	ds_read_b128 v[152:155], v221 offset:2048
	ds_read_b128 v[156:159], v221 offset:3072
	ds_read_b128 v[160:163], v221 offset:4096
	ds_read_b128 v[164:167], v221 offset:5120
	ds_read_b128 v[168:171], v221 offset:6144
	ds_read_b128 v[172:175], v221 offset:7168
	global_load_lds_dwordx4 v200, s[0:1]
	s_add_i32 m0, s50, 0xe000
	s_nop 0
	global_load_lds_dwordx4 v198, s[0:1]
	s_waitcnt lgkmcnt(8)
	s_barrier
	s_waitcnt lgkmcnt(0)
	s_waitcnt lgkmcnt(0)
	v_mfma_f32_16x16x32_bf16 v[120:123], v[128:131], v[144:147], v[120:123]
	v_mfma_f32_16x16x32_bf16 v[112:115], v[136:139], v[144:147], v[112:115]
	v_mfma_f32_16x16x32_bf16 v[104:107], v[128:131], v[152:155], v[104:107]
	v_mfma_f32_16x16x32_bf16 v[96:99], v[136:139], v[152:155], v[96:99]
	v_mfma_f32_16x16x32_bf16 v[88:91], v[128:131], v[160:163], v[88:91]
	v_mfma_f32_16x16x32_bf16 v[80:83], v[136:139], v[160:163], v[80:83]
	v_mfma_f32_16x16x32_bf16 v[72:75], v[128:131], v[168:171], v[72:75]
	v_mfma_f32_16x16x32_bf16 v[64:67], v[136:139], v[168:171], v[64:67]
	v_mfma_f32_16x16x32_bf16 v[120:123], v[132:135], v[148:151], v[120:123]
	v_mfma_f32_16x16x32_bf16 v[112:115], v[140:143], v[148:151], v[112:115]
	v_mfma_f32_16x16x32_bf16 v[104:107], v[132:135], v[156:159], v[104:107]
	v_mfma_f32_16x16x32_bf16 v[96:99], v[140:143], v[156:159], v[96:99]
	v_mfma_f32_16x16x32_bf16 v[88:91], v[132:135], v[164:167], v[88:91]
	v_mfma_f32_16x16x32_bf16 v[80:83], v[140:143], v[164:167], v[80:83]
	v_mfma_f32_16x16x32_bf16 v[72:75], v[132:135], v[172:175], v[72:75]
	v_mfma_f32_16x16x32_bf16 v[64:67], v[140:143], v[172:175], v[64:67]
	s_barrier
	s_add_i32 s33, 0, 0x14000
	s_add_i32 s31, s31, s34
	s_mov_b32 m0, s31
	ds_read_b128 v[176:179], v241
	ds_read_b128 v[180:183], v241 offset:1024
	ds_read_b128 v[184:187], v241 offset:2048
	ds_read_b128 v[202:205], v241 offset:3072
	s_add_u32 s36, s28, 0x80
	s_addc_u32 s37, s29, 0
	global_load_lds_dwordx4 v192, s[28:29]
	s_add_i32 m0, s31, 0x2000
	s_nop 0
	global_load_lds_dwordx4 v194, s[28:29]
	s_waitcnt vmcnt(10)
	s_barrier
	s_waitcnt lgkmcnt(0)
	s_waitcnt lgkmcnt(0)
	v_mfma_f32_16x16x32_bf16 v[124:127], v[176:179], v[144:147], v[124:127]
	v_mfma_f32_16x16x32_bf16 v[116:119], v[184:187], v[144:147], v[116:119]
	v_mfma_f32_16x16x32_bf16 v[108:111], v[176:179], v[152:155], v[108:111]
	v_mfma_f32_16x16x32_bf16 v[100:103], v[184:187], v[152:155], v[100:103]
	v_mfma_f32_16x16x32_bf16 v[92:95], v[176:179], v[160:163], v[92:95]
	v_mfma_f32_16x16x32_bf16 v[84:87], v[184:187], v[160:163], v[84:87]
	v_mfma_f32_16x16x32_bf16 v[76:79], v[176:179], v[168:171], v[76:79]
	v_mfma_f32_16x16x32_bf16 v[68:71], v[184:187], v[168:171], v[68:71]
	v_mfma_f32_16x16x32_bf16 v[124:127], v[180:183], v[148:151], v[124:127]
	v_mfma_f32_16x16x32_bf16 v[116:119], v[202:205], v[148:151], v[116:119]
	v_mfma_f32_16x16x32_bf16 v[108:111], v[180:183], v[156:159], v[108:111]
	v_mfma_f32_16x16x32_bf16 v[100:103], v[202:205], v[156:159], v[100:103]
	v_mfma_f32_16x16x32_bf16 v[92:95], v[180:183], v[164:167], v[92:95]
	v_mfma_f32_16x16x32_bf16 v[84:87], v[202:205], v[164:167], v[84:87]
	v_mfma_f32_16x16x32_bf16 v[76:79], v[180:183], v[172:175], v[76:79]
	v_mfma_f32_16x16x32_bf16 v[68:71], v[202:205], v[172:175], v[68:71]
	s_mov_b32 m0, s50
	s_barrier
	ds_read_b128 v[144:147], v221 offset:16384
	ds_read_b128 v[148:151], v221 offset:17408
	ds_read_b128 v[152:155], v221 offset:18432
	ds_read_b128 v[156:159], v221 offset:19456
	ds_read_b128 v[160:163], v221 offset:20480
	ds_read_b128 v[164:167], v221 offset:21504
	ds_read_b128 v[168:171], v221 offset:22528
	ds_read_b128 v[172:175], v221 offset:23552
	s_add_u32 s54, s4, 0x80
	s_addc_u32 s55, s5, 0
	global_load_lds_dwordx4 v192, s[4:5]
	s_mov_b32 m0, s51
	s_nop 0
	global_load_lds_dwordx4 v194, s[4:5]
	s_barrier
	s_waitcnt lgkmcnt(0)
	s_waitcnt lgkmcnt(0)
	v_mfma_f32_16x16x32_bf16 v[60:63], v[128:131], v[144:147], v[60:63]
	v_mfma_f32_16x16x32_bf16 v[52:55], v[136:139], v[144:147], v[52:55]
	v_mfma_f32_16x16x32_bf16 v[44:47], v[128:131], v[152:155], v[44:47]
	v_mfma_f32_16x16x32_bf16 v[36:39], v[136:139], v[152:155], v[36:39]
	v_mfma_f32_16x16x32_bf16 v[28:31], v[128:131], v[160:163], v[28:31]
	v_mfma_f32_16x16x32_bf16 v[20:23], v[136:139], v[160:163], v[20:23]
	v_mfma_f32_16x16x32_bf16 v[12:15], v[128:131], v[168:171], v[12:15]
	v_mfma_f32_16x16x32_bf16 v[4:7], v[136:139], v[168:171], v[4:7]
	v_mfma_f32_16x16x32_bf16 v[60:63], v[132:135], v[148:151], v[60:63]
	v_mfma_f32_16x16x32_bf16 v[52:55], v[140:143], v[148:151], v[52:55]
	v_mfma_f32_16x16x32_bf16 v[44:47], v[132:135], v[156:159], v[44:47]
	v_mfma_f32_16x16x32_bf16 v[36:39], v[140:143], v[156:159], v[36:39]
	v_mfma_f32_16x16x32_bf16 v[28:31], v[132:135], v[164:167], v[28:31]
	v_mfma_f32_16x16x32_bf16 v[20:23], v[140:143], v[164:167], v[20:23]
	v_mfma_f32_16x16x32_bf16 v[12:15], v[132:135], v[172:175], v[12:15]
	v_mfma_f32_16x16x32_bf16 v[4:7], v[140:143], v[172:175], v[4:7]
	s_barrier
	s_add_u32 s28, s28, s20
	s_addc_u32 s29, s29, s21
	s_add_u32 s84, s28, 0x80
	s_addc_u32 s85, s29, 0
	s_add_i32 s31, s33, s34
	s_mov_b32 m0, s31
	s_nop 0
	global_load_lds_dwordx4 v192, s[28:29]
	s_add_i32 m0, s31, 0x2000
	s_nop 0
	global_load_lds_dwordx4 v194, s[28:29]
	s_waitcnt vmcnt(8)
	s_barrier
; #define PG8_STAGE(bufoff, gbase, voff) do { _Pragma("unroll") for (int _i = 0; _i < 2; ++_i) \
;         __builtin_amdgcn_global_load_lds((const unsigned*)((const char*)(gbase) + (voff)[_i]), (LAS unsigned*)(lds + (bufoff) + ldsw + _i * 8192), 16, 0, 0); } while (0)
; #define PG8_LDA(dst, b, h) do { _Pragma("unroll") for (int m = 0; m < 4; ++m) _Pragma("unroll") for (int k = 0; k < 2; ++k) dst[m][k] = *(const LAS bf16x8*)(lds + PG8_SA(b, h) + aoff + m * 2048 + k * 1024); } while (0)
; #define PG8_LDB(dst, b, h) do { _Pragma("unroll") for (int n = 0; n < 2; ++n) _Pragma("unroll") for (int k = 0; k < 2; ++k) dst[n][k] = *(const LAS bf16x8*)(lds + PG8_SB(b, h) + boff + n * 2048 + k * 1024); } while (0)
; #define PG8_MMA(ai, bj, At, Bt) do { __builtin_amdgcn_s_setprio(1); _Pragma("unroll") for (int m = 0; m < 4; ++m) _Pragma("unroll") for (int n = 0; n < 2; ++n) _Pragma("unroll") for (int k = 0; k < 2; ++k) \
;         acc[ai][bj][m][n] = __builtin_amdgcn_mfma_f32_16x16x32_bf16(Bt[n][k], At[m][k], acc[ai][bj][m][n], 0, 0, 0); __builtin_amdgcn_s_setprio(0); } while (0)
; #define PG8_WAIT_V(n) asm volatile("s_waitcnt vmcnt(" #n ")" ::: "memory")
; #define PG8_WAIT_L(n) asm volatile("s_waitcnt lgkmcnt(" #n ")" ::: "memory")
; #define PG8_BAR __builtin_amdgcn_s_barrier()
; #define PG8_SCHED __builtin_amdgcn_sched_barrier(0)
; template <class Epi, class Sched>
; __device__ __forceinline__ void gemm_phase(LAS unsigned char* lds, const Gemm g, const Sched& S, const Epi& E) {
;     ...
;             PG8_WAIT_V(6); PG8_BAR; PG8_MMA(1, 1, At, B1); PG8_BAR;
;             PG8_LDB(B0, 1, 0); PG8_SCHED; PG8_LDA(At, 1, 0); PG8_STAGE(PG8_SA(0, 1), a2 + hstep, voffA);
;             PG8_WAIT_L(8); PG8_BAR; PG8_WAIT_L(0); PG8_MMA(0, 0, At, B0); PG8_BAR; PG8_SCHED;
;             PG8_LDB(B1, 1, 1); PG8_STAGE(PG8_SB(1, 0), b3, voffB);
	v_mfma_f32_16x16x32_bf16 v[56:59], v[176:179], v[144:147], v[56:59]
	v_mfma_f32_16x16x32_bf16 v[48:51], v[184:187], v[144:147], v[48:51]
	v_mfma_f32_16x16x32_bf16 v[40:43], v[176:179], v[152:155], v[40:43]
	v_mfma_f32_16x16x32_bf16 v[32:35], v[184:187], v[152:155], v[32:35]
	v_mfma_f32_16x16x32_bf16 v[24:27], v[176:179], v[160:163], v[24:27]
	v_mfma_f32_16x16x32_bf16 v[16:19], v[184:187], v[160:163], v[16:19]
	v_mfma_f32_16x16x32_bf16 v[8:11], v[176:179], v[168:171], v[8:11]
	v_mfma_f32_16x16x32_bf16 v[0:3], v[184:187], v[168:171], v[0:3]
	v_mfma_f32_16x16x32_bf16 v[56:59], v[180:183], v[148:151], v[56:59]
	v_mfma_f32_16x16x32_bf16 v[48:51], v[202:205], v[148:151], v[48:51]
	v_mfma_f32_16x16x32_bf16 v[40:43], v[180:183], v[156:159], v[40:43]
	v_mfma_f32_16x16x32_bf16 v[32:35], v[202:205], v[156:159], v[32:35]
	v_mfma_f32_16x16x32_bf16 v[24:27], v[180:183], v[164:167], v[24:27]
	v_mfma_f32_16x16x32_bf16 v[16:19], v[202:205], v[164:167], v[16:19]
	v_mfma_f32_16x16x32_bf16 v[8:11], v[180:183], v[172:175], v[8:11]
	v_mfma_f32_16x16x32_bf16 v[0:3], v[202:205], v[172:175], v[0:3]
	s_add_i32 s28, 0, 0x18000
	s_barrier
	ds_read_b128 v[128:131], v242
	ds_read_b128 v[132:135], v242 offset:1024
	ds_read_b128 v[136:139], v242 offset:2048
	ds_read_b128 v[140:143], v242 offset:3072
	s_add_u32 s4, s4, s20
	s_addc_u32 s5, s5, s21
	s_mov_b32 m0, s60
	ds_read_b128 v[144:147], v221 offset:32768
	ds_read_b128 v[148:151], v221 offset:33792
	ds_read_b128 v[152:155], v221 offset:34816
	ds_read_b128 v[156:159], v221 offset:35840
	ds_read_b128 v[160:163], v221 offset:36864
	ds_read_b128 v[164:167], v221 offset:37888
	ds_read_b128 v[168:171], v221 offset:38912
	ds_read_b128 v[172:175], v221 offset:39936
	global_load_lds_dwordx4 v192, s[4:5]
	s_mov_b32 m0, s61
	s_nop 0
	global_load_lds_dwordx4 v194, s[4:5]
	s_waitcnt lgkmcnt(8)
	s_barrier
	s_waitcnt lgkmcnt(0)
	s_waitcnt lgkmcnt(0)
	v_mfma_f32_16x16x32_bf16 v[120:123], v[128:131], v[144:147], v[120:123]
	v_mfma_f32_16x16x32_bf16 v[112:115], v[136:139], v[144:147], v[112:115]
	v_mfma_f32_16x16x32_bf16 v[104:107], v[128:131], v[152:155], v[104:107]
	v_mfma_f32_16x16x32_bf16 v[96:99], v[136:139], v[152:155], v[96:99]
	v_mfma_f32_16x16x32_bf16 v[88:91], v[128:131], v[160:163], v[88:91]
	v_mfma_f32_16x16x32_bf16 v[80:83], v[136:139], v[160:163], v[80:83]
	v_mfma_f32_16x16x32_bf16 v[72:75], v[128:131], v[168:171], v[72:75]
	v_mfma_f32_16x16x32_bf16 v[64:67], v[136:139], v[168:171], v[64:67]
	v_mfma_f32_16x16x32_bf16 v[120:123], v[132:135], v[148:151], v[120:123]
	v_mfma_f32_16x16x32_bf16 v[112:115], v[140:143], v[148:151], v[112:115]
	v_mfma_f32_16x16x32_bf16 v[104:107], v[132:135], v[156:159], v[104:107]
	v_mfma_f32_16x16x32_bf16 v[96:99], v[140:143], v[156:159], v[96:99]
	v_mfma_f32_16x16x32_bf16 v[88:91], v[132:135], v[164:167], v[88:91]
	v_mfma_f32_16x16x32_bf16 v[80:83], v[140:143], v[164:167], v[80:83]
	v_mfma_f32_16x16x32_bf16 v[72:75], v[132:135], v[172:175], v[72:75]
	v_mfma_f32_16x16x32_bf16 v[64:67], v[140:143], v[172:175], v[64:67]
	s_barrier
	s_add_i32 s4, 0, 0x1c000
	s_add_i32 s5, s28, s34
	s_mov_b32 m0, s5
	ds_read_b128 v[176:179], v243
	ds_read_b128 v[180:183], v243 offset:1024
	ds_read_b128 v[184:187], v243 offset:2048
	ds_read_b128 v[202:205], v243 offset:3072
	global_load_lds_dwordx4 v192, s[36:37]
	s_add_i32 m0, s5, 0x2000
	s_nop 0
	global_load_lds_dwordx4 v194, s[36:37]
	s_waitcnt vmcnt(10)
	s_barrier
; #define PG8_STAGE(bufoff, gbase, voff) do { _Pragma("unroll") for (int _i = 0; _i < 2; ++_i) \
;         __builtin_amdgcn_global_load_lds((const unsigned*)((const char*)(gbase) + (voff)[_i]), (LAS unsigned*)(lds + (bufoff) + ldsw + _i * 8192), 16, 0, 0); } while (0)
; #define PG8_LDA(dst, b, h) do { _Pragma("unroll") for (int m = 0; m < 4; ++m) _Pragma("unroll") for (int k = 0; k < 2; ++k) dst[m][k] = *(const LAS bf16x8*)(lds + PG8_SA(b, h) + aoff + m * 2048 + k * 1024); } while (0)
; #define PG8_LDB(dst, b, h) do { _Pragma("unroll") for (int n = 0; n < 2; ++n) _Pragma("unroll") for (int k = 0; k < 2; ++k) dst[n][k] = *(const LAS bf16x8*)(lds + PG8_SB(b, h) + boff + n * 2048 + k * 1024); } while (0)
; #define PG8_MMA(ai, bj, At, Bt) do { __builtin_amdgcn_s_setprio(1); _Pragma("unroll") for (int m = 0; m < 4; ++m) _Pragma("unroll") for (int n = 0; n < 2; ++n) _Pragma("unroll") for (int k = 0; k < 2; ++k) \
;         acc[ai][bj][m][n] = __builtin_amdgcn_mfma_f32_16x16x32_bf16(Bt[n][k], At[m][k], acc[ai][bj][m][n], 0, 0, 0); __builtin_amdgcn_s_setprio(0); } while (0)
; #define PG8_WAIT_V(n) asm volatile("s_waitcnt vmcnt(" #n ")" ::: "memory")
; #define PG8_WAIT_L(n) asm volatile("s_waitcnt lgkmcnt(" #n ")" ::: "memory")
; #define PG8_BAR __builtin_amdgcn_s_barrier()
; #define PG8_SCHED __builtin_amdgcn_sched_barrier(0)
; template <class Epi, class Sched>
; __device__ __forceinline__ void gemm_phase(LAS unsigned char* lds, const Gemm g, const Sched& S, const Epi& E) {
;     ...
;             PG8_LDB(B1, 1, 1); PG8_STAGE(PG8_SB(1, 0), b3, voffB);
;             PG8_BAR; PG8_WAIT_L(0); PG8_MMA(0, 1, At, B1); PG8_BAR;
;             PG8_LDA(At, 1, 1); PG8_STAGE(PG8_SA(1, 0), a3, voffA);
;             PG8_BAR; PG8_WAIT_L(0); PG8_MMA(1, 0, At, B0); PG8_BAR; PG8_SCHED;
;             PG8_STAGE(PG8_SB(1, 1), b3 + hstep, voffB);
;             PG8_WAIT_V(6); PG8_BAR; PG8_MMA(1, 1, At, B1); PG8_BAR;
;         }
	s_waitcnt lgkmcnt(0)
	s_waitcnt lgkmcnt(0)
	v_mfma_f32_16x16x32_bf16 v[124:127], v[176:179], v[144:147], v[124:127]
	v_mfma_f32_16x16x32_bf16 v[116:119], v[184:187], v[144:147], v[116:119]
	v_mfma_f32_16x16x32_bf16 v[108:111], v[176:179], v[152:155], v[108:111]
	v_mfma_f32_16x16x32_bf16 v[100:103], v[184:187], v[152:155], v[100:103]
	v_mfma_f32_16x16x32_bf16 v[92:95], v[176:179], v[160:163], v[92:95]
	v_mfma_f32_16x16x32_bf16 v[84:87], v[184:187], v[160:163], v[84:87]
	v_mfma_f32_16x16x32_bf16 v[76:79], v[176:179], v[168:171], v[76:79]
	v_mfma_f32_16x16x32_bf16 v[68:71], v[184:187], v[168:171], v[68:71]
	v_mfma_f32_16x16x32_bf16 v[124:127], v[180:183], v[148:151], v[124:127]
	v_mfma_f32_16x16x32_bf16 v[116:119], v[202:205], v[148:151], v[116:119]
	v_mfma_f32_16x16x32_bf16 v[108:111], v[180:183], v[156:159], v[108:111]
	v_mfma_f32_16x16x32_bf16 v[100:103], v[202:205], v[156:159], v[100:103]
	v_mfma_f32_16x16x32_bf16 v[92:95], v[180:183], v[164:167], v[92:95]
	v_mfma_f32_16x16x32_bf16 v[84:87], v[202:205], v[164:167], v[84:87]
	v_mfma_f32_16x16x32_bf16 v[76:79], v[180:183], v[172:175], v[76:79]
	v_mfma_f32_16x16x32_bf16 v[68:71], v[202:205], v[172:175], v[68:71]
	s_mov_b32 m0, s62
	s_barrier
	ds_read_b128 v[144:147], v221 offset:49152
	ds_read_b128 v[148:151], v221 offset:50176
	ds_read_b128 v[152:155], v221 offset:51200
	ds_read_b128 v[156:159], v221 offset:52224
	ds_read_b128 v[160:163], v221 offset:53248
	ds_read_b128 v[164:167], v221 offset:54272
	ds_read_b128 v[168:171], v221 offset:55296
	ds_read_b128 v[172:175], v221 offset:56320
	global_load_lds_dwordx4 v192, s[54:55]
	s_mov_b32 m0, s63
	s_nop 0
	global_load_lds_dwordx4 v194, s[54:55]
	s_barrier
	s_waitcnt lgkmcnt(0)
	s_waitcnt lgkmcnt(0)
	v_mfma_f32_16x16x32_bf16 v[60:63], v[128:131], v[144:147], v[60:63]
	v_mfma_f32_16x16x32_bf16 v[52:55], v[136:139], v[144:147], v[52:55]
	v_mfma_f32_16x16x32_bf16 v[44:47], v[128:131], v[152:155], v[44:47]
	v_mfma_f32_16x16x32_bf16 v[36:39], v[136:139], v[152:155], v[36:39]
	v_mfma_f32_16x16x32_bf16 v[28:31], v[128:131], v[160:163], v[28:31]
	v_mfma_f32_16x16x32_bf16 v[20:23], v[136:139], v[160:163], v[20:23]
	v_mfma_f32_16x16x32_bf16 v[12:15], v[128:131], v[168:171], v[12:15]
	v_mfma_f32_16x16x32_bf16 v[4:7], v[136:139], v[168:171], v[4:7]
	v_mfma_f32_16x16x32_bf16 v[60:63], v[132:135], v[148:151], v[60:63]
	v_mfma_f32_16x16x32_bf16 v[52:55], v[140:143], v[148:151], v[52:55]
	v_mfma_f32_16x16x32_bf16 v[44:47], v[132:135], v[156:159], v[44:47]
	v_mfma_f32_16x16x32_bf16 v[36:39], v[140:143], v[156:159], v[36:39]
	v_mfma_f32_16x16x32_bf16 v[28:31], v[132:135], v[164:167], v[28:31]
	v_mfma_f32_16x16x32_bf16 v[20:23], v[140:143], v[164:167], v[20:23]
	v_mfma_f32_16x16x32_bf16 v[12:15], v[132:135], v[172:175], v[12:15]
	v_mfma_f32_16x16x32_bf16 v[4:7], v[140:143], v[172:175], v[4:7]
	s_barrier
	s_add_i32 s4, s4, s34
	s_mov_b32 m0, s4
	s_nop 0
	global_load_lds_dwordx4 v192, s[84:85]
	s_add_i32 m0, s4, 0x2000
	s_nop 0
	global_load_lds_dwordx4 v194, s[84:85]
	s_waitcnt vmcnt(8)
	s_barrier
	v_mfma_f32_16x16x32_bf16 v[56:59], v[176:179], v[144:147], v[56:59]
	v_mfma_f32_16x16x32_bf16 v[48:51], v[184:187], v[144:147], v[48:51]
	v_mfma_f32_16x16x32_bf16 v[40:43], v[176:179], v[152:155], v[40:43]
	v_mfma_f32_16x16x32_bf16 v[32:35], v[184:187], v[152:155], v[32:35]
	v_mfma_f32_16x16x32_bf16 v[24:27], v[176:179], v[160:163], v[24:27]
	v_mfma_f32_16x16x32_bf16 v[16:19], v[184:187], v[160:163], v[16:19]
	v_mfma_f32_16x16x32_bf16 v[8:11], v[176:179], v[168:171], v[8:11]
	v_mfma_f32_16x16x32_bf16 v[0:3], v[184:187], v[168:171], v[0:3]
	v_mfma_f32_16x16x32_bf16 v[56:59], v[180:183], v[148:151], v[56:59]
	v_mfma_f32_16x16x32_bf16 v[48:51], v[202:205], v[148:151], v[48:51]
	v_mfma_f32_16x16x32_bf16 v[40:43], v[180:183], v[156:159], v[40:43]
	v_mfma_f32_16x16x32_bf16 v[32:35], v[202:205], v[156:159], v[32:35]
	v_mfma_f32_16x16x32_bf16 v[24:27], v[180:183], v[164:167], v[24:27]
	v_mfma_f32_16x16x32_bf16 v[16:19], v[202:205], v[164:167], v[16:19]
	v_mfma_f32_16x16x32_bf16 v[8:11], v[180:183], v[172:175], v[8:11]
	v_mfma_f32_16x16x32_bf16 v[0:3], v[202:205], v[172:175], v[0:3]
	s_add_u32 s75, s75, 0x100
	s_addc_u32 s76, s76, 0
	s_add_u32 s0, s0, 0x100
	s_addc_u32 s1, s1, 0
	s_cmp_ge_i32 s30, s13
	s_mov_b32 s4, s30
	s_barrier
	s_cbranch_scc0 .LBB0_339
	s_mov_b32 s33, 0x200000
	s_cmp_lt_i32 s15, 2
	s_cbranch_scc1 .LBB0_345
